# lever 7: per-tile cross-half row-max exchange via v_permlane32_swap instead of ds_bpermute LDS round trip (11 flash-loop sites)
# speedup vs baseline: 1.0687x; 1.0044x over previous
.LBB0_183:
	s_or_b64 exec, exec, s[0:1]
	v_mbcnt_hi_u32_b32 v3, -1, v227
	v_and_b32_e32 v5, 64, v3
	v_xor_b32_e32 v4, 32, v3
	v_add_u32_e32 v5, 64, v5
	v_cmp_lt_i32_e32 vcc, v4, v5
	s_mov_b32 s0, 0x41000000
	s_nop 0
	v_cndmask_b32_e32 v3, v3, v4, vcc
	v_lshlrev_b32_e32 v3, 2, v3
	v_max_f32_e32 v2, v2, v2
	s_waitcnt lgkmcnt(0)
	v_mov_b32_e32 v3, v2
	s_nop 1
	v_permlane32_swap_b32_e32 v2, v3
	v_max_f32_e32 v2, v2, v3
	v_sub_f32_e32 v3, v2, v151
	v_cmp_lt_f32_e32 vcc, s0, v3
	s_cbranch_vccz .LBB0_185
	v_max_f32_e32 v2, v2, v2
	v_max_f32_e32 v3, v151, v151
	v_max_f32_e32 v3, v3, v2
	v_cmp_neq_f32_e32 vcc, s33, v3
	s_nop 1
	v_cndmask_b32_e32 v2, 0, v3, vcc
	v_sub_f32_e32 v2, v151, v2
	v_exp_f32_e32 v2, v2
	v_mov_b32_e32 v151, v3
	v_mul_f32_e32 v217, v217, v2
	v_pk_mul_f32 v[64:65], v[64:65], v[2:3] op_sel_hi:[1,0]
	v_pk_mul_f32 v[62:63], v[62:63], v[2:3] op_sel_hi:[1,0]
	v_pk_mul_f32 v[60:61], v[60:61], v[2:3] op_sel_hi:[1,0]
	v_pk_mul_f32 v[58:59], v[58:59], v[2:3] op_sel_hi:[1,0]
	v_pk_mul_f32 v[56:57], v[56:57], v[2:3] op_sel_hi:[1,0]
	v_pk_mul_f32 v[54:55], v[54:55], v[2:3] op_sel_hi:[1,0]
	v_pk_mul_f32 v[52:53], v[52:53], v[2:3] op_sel_hi:[1,0]
	v_pk_mul_f32 v[50:51], v[50:51], v[2:3] op_sel_hi:[1,0]
	v_pk_mul_f32 v[48:49], v[48:49], v[2:3] op_sel_hi:[1,0]
	v_pk_mul_f32 v[46:47], v[46:47], v[2:3] op_sel_hi:[1,0]
	v_pk_mul_f32 v[44:45], v[44:45], v[2:3] op_sel_hi:[1,0]
	v_pk_mul_f32 v[42:43], v[42:43], v[2:3] op_sel_hi:[1,0]
	v_pk_mul_f32 v[40:41], v[40:41], v[2:3] op_sel_hi:[1,0]
	v_pk_mul_f32 v[38:39], v[38:39], v[2:3] op_sel_hi:[1,0]
	v_pk_mul_f32 v[36:37], v[36:37], v[2:3] op_sel_hi:[1,0]
	v_pk_mul_f32 v[34:35], v[34:35], v[2:3] op_sel_hi:[1,0]

.LBB0_216:
	s_or_b64 exec, exec, s[0:1]
	v_max_f32_e32 v0, v0, v0
	s_mov_b32 s0, 0x41000000
	s_waitcnt lgkmcnt(0)
	v_mov_b32_e32 v2, v0
	s_nop 1
	v_permlane32_swap_b32_e32 v0, v2
	v_max_f32_e32 v0, v0, v2
	v_sub_f32_e32 v2, v0, v226
	v_cmp_lt_f32_e32 vcc, s0, v2
	s_cbranch_vccz .LBB0_218
	v_max_f32_e32 v0, v0, v0
	v_max_f32_e32 v2, v226, v226
	v_max_f32_e32 v2, v2, v0
	v_cmp_neq_f32_e32 vcc, s33, v2
	s_nop 1
	v_cndmask_b32_e32 v0, 0, v2, vcc
	v_sub_f32_e32 v0, v226, v0
	v_exp_f32_e32 v0, v0
	v_mov_b32_e32 v226, v2
	v_mul_f32_e32 v183, v183, v0
	v_pk_mul_f32 v[96:97], v[96:97], v[0:1] op_sel_hi:[1,0]
	v_pk_mul_f32 v[94:95], v[94:95], v[0:1] op_sel_hi:[1,0]
	v_pk_mul_f32 v[92:93], v[92:93], v[0:1] op_sel_hi:[1,0]
	v_pk_mul_f32 v[90:91], v[90:91], v[0:1] op_sel_hi:[1,0]
	v_pk_mul_f32 v[88:89], v[88:89], v[0:1] op_sel_hi:[1,0]
	v_pk_mul_f32 v[86:87], v[86:87], v[0:1] op_sel_hi:[1,0]
	v_pk_mul_f32 v[84:85], v[84:85], v[0:1] op_sel_hi:[1,0]
	v_pk_mul_f32 v[82:83], v[82:83], v[0:1] op_sel_hi:[1,0]
	v_pk_mul_f32 v[80:81], v[80:81], v[0:1] op_sel_hi:[1,0]
	v_pk_mul_f32 v[78:79], v[78:79], v[0:1] op_sel_hi:[1,0]
	v_pk_mul_f32 v[76:77], v[76:77], v[0:1] op_sel_hi:[1,0]
	v_pk_mul_f32 v[74:75], v[74:75], v[0:1] op_sel_hi:[1,0]
	v_pk_mul_f32 v[72:73], v[72:73], v[0:1] op_sel_hi:[1,0]
	v_pk_mul_f32 v[70:71], v[70:71], v[0:1] op_sel_hi:[1,0]
	v_pk_mul_f32 v[68:69], v[68:69], v[0:1] op_sel_hi:[1,0]
	v_pk_mul_f32 v[66:67], v[66:67], v[0:1] op_sel_hi:[1,0]

.LBB0_256:
	s_or_b64 exec, exec, s[2:3]
	v_mbcnt_hi_u32_b32 v34, -1, v227
	v_and_b32_e32 v36, 64, v34
	v_xor_b32_e32 v35, 32, v34
	v_add_u32_e32 v36, 64, v36
	v_cmp_lt_i32_e32 vcc, v35, v36
	s_mov_b32 s2, 0x41000000
	s_nop 0
	v_cndmask_b32_e32 v34, v34, v35, vcc
	v_lshlrev_b32_e32 v34, 2, v34
	v_max_f32_e32 v0, v0, v0
	s_waitcnt lgkmcnt(0)
	v_mov_b32_e32 v34, v0
	s_nop 1
	v_permlane32_swap_b32_e32 v0, v34
	v_max_f32_e32 v0, v0, v34
	v_sub_f32_e32 v34, v0, v197
	v_cmp_lt_f32_e32 vcc, s2, v34
	s_cbranch_vccz .LBB0_258
	v_max_f32_e32 v0, v0, v0
	v_max_f32_e32 v34, v197, v197
	v_max_f32_e32 v34, v34, v0
	v_cmp_neq_f32_e32 vcc, s33, v34
	s_nop 1
	v_cndmask_b32_e32 v0, 0, v34, vcc
	v_sub_f32_e32 v0, v197, v0
	v_exp_f32_e32 v0, v0
	v_mov_b32_e32 v197, v34
	v_mul_f32_e32 v179, v179, v0
	v_pk_mul_f32 v[32:33], v[32:33], v[0:1] op_sel_hi:[1,0]
	v_pk_mul_f32 v[30:31], v[30:31], v[0:1] op_sel_hi:[1,0]
	v_pk_mul_f32 v[28:29], v[28:29], v[0:1] op_sel_hi:[1,0]
	v_pk_mul_f32 v[26:27], v[26:27], v[0:1] op_sel_hi:[1,0]
	v_pk_mul_f32 v[24:25], v[24:25], v[0:1] op_sel_hi:[1,0]
	v_pk_mul_f32 v[22:23], v[22:23], v[0:1] op_sel_hi:[1,0]
	v_pk_mul_f32 v[20:21], v[20:21], v[0:1] op_sel_hi:[1,0]
	v_pk_mul_f32 v[18:19], v[18:19], v[0:1] op_sel_hi:[1,0]
	v_pk_mul_f32 v[16:17], v[16:17], v[0:1] op_sel_hi:[1,0]
	v_pk_mul_f32 v[14:15], v[14:15], v[0:1] op_sel_hi:[1,0]
	v_pk_mul_f32 v[12:13], v[12:13], v[0:1] op_sel_hi:[1,0]
	v_pk_mul_f32 v[10:11], v[10:11], v[0:1] op_sel_hi:[1,0]
	v_pk_mul_f32 v[8:9], v[8:9], v[0:1] op_sel_hi:[1,0]
	v_pk_mul_f32 v[6:7], v[6:7], v[0:1] op_sel_hi:[1,0]
	v_pk_mul_f32 v[4:5], v[4:5], v[0:1] op_sel_hi:[1,0]
	v_pk_mul_f32 v[2:3], v[2:3], v[0:1] op_sel_hi:[1,0]

.LBB0_267:
	s_or_b64 exec, exec, s[2:3]
	v_mbcnt_hi_u32_b32 v166, -1, v227
	v_and_b32_e32 v35, 64, v166
	v_xor_b32_e32 v0, 32, v166
	v_add_u32_e32 v167, 64, v35
	v_cmp_lt_i32_e32 vcc, v0, v167
	s_mov_b32 s2, 0x41000000
	s_nop 0
	v_cndmask_b32_e32 v35, v166, v0, vcc
	v_lshlrev_b32_e32 v35, 2, v35
	v_max_f32_e32 v34, v34, v34
	s_waitcnt lgkmcnt(0)
	v_mov_b32_e32 v35, v34
	s_nop 1
	v_permlane32_swap_b32_e32 v34, v35
	v_max_f32_e32 v34, v34, v35
	v_sub_f32_e32 v35, v34, v197
	v_cmp_lt_f32_e32 vcc, s2, v35
	s_cbranch_vccz .LBB0_269
	v_max_f32_e32 v34, v34, v34
	v_max_f32_e32 v35, v197, v197
	v_max_f32_e32 v66, v35, v34
	v_cmp_neq_f32_e32 vcc, s33, v66
	s_nop 1
	v_cndmask_b32_e32 v34, 0, v66, vcc
	v_sub_f32_e32 v34, v197, v34
	v_exp_f32_e32 v34, v34
	v_mov_b32_e32 v197, v66
	v_mul_f32_e32 v130, v179, v34
	v_pk_mul_f32 v[64:65], v[32:33], v[34:35] op_sel_hi:[1,0]
	v_pk_mul_f32 v[62:63], v[30:31], v[34:35] op_sel_hi:[1,0]
	v_pk_mul_f32 v[60:61], v[28:29], v[34:35] op_sel_hi:[1,0]
	v_pk_mul_f32 v[58:59], v[26:27], v[34:35] op_sel_hi:[1,0]
	v_pk_mul_f32 v[56:57], v[24:25], v[34:35] op_sel_hi:[1,0]
	v_pk_mul_f32 v[54:55], v[22:23], v[34:35] op_sel_hi:[1,0]
	v_pk_mul_f32 v[52:53], v[20:21], v[34:35] op_sel_hi:[1,0]
	v_pk_mul_f32 v[50:51], v[18:19], v[34:35] op_sel_hi:[1,0]
	v_pk_mul_f32 v[48:49], v[16:17], v[34:35] op_sel_hi:[1,0]
	v_pk_mul_f32 v[46:47], v[14:15], v[34:35] op_sel_hi:[1,0]
	v_pk_mul_f32 v[44:45], v[12:13], v[34:35] op_sel_hi:[1,0]
	v_pk_mul_f32 v[42:43], v[10:11], v[34:35] op_sel_hi:[1,0]
	v_pk_mul_f32 v[40:41], v[8:9], v[34:35] op_sel_hi:[1,0]
	v_pk_mul_f32 v[38:39], v[6:7], v[34:35] op_sel_hi:[1,0]
	v_pk_mul_f32 v[36:37], v[4:5], v[34:35] op_sel_hi:[1,0]
	v_pk_mul_f32 v[34:35], v[2:3], v[34:35] op_sel_hi:[1,0]
	s_branch .LBB0_270

.LBB0_290:
	s_or_b64 exec, exec, s[8:9]
	v_and_b32_e32 v4, 64, v228
	v_xor_b32_e32 v3, 32, v228
	v_add_u32_e32 v4, 64, v4
	v_cmp_lt_i32_e32 vcc, v3, v4
	s_mov_b32 s8, 0x41000000
	s_nop 0
	v_cndmask_b32_e32 v3, v228, v3, vcc
	v_lshlrev_b32_e32 v3, 2, v3
	v_max_f32_e32 v2, v2, v2
	s_waitcnt lgkmcnt(0)
	v_mov_b32_e32 v3, v2
	s_nop 1
	v_permlane32_swap_b32_e32 v2, v3
	v_max_f32_e32 v2, v2, v3
	v_sub_f32_e32 v3, v2, v200
	v_cmp_lt_f32_e32 vcc, s8, v3
	s_cbranch_vccz .LBB0_292
	v_max_f32_e32 v2, v2, v2
	v_max_f32_e32 v3, v200, v200
	v_max_f32_e32 v3, v3, v2
	v_cmp_neq_f32_e32 vcc, s33, v3
	s_nop 1
	v_cndmask_b32_e32 v2, 0, v3, vcc
	v_sub_f32_e32 v2, v200, v2
	v_exp_f32_e32 v2, v2
	v_mov_b32_e32 v200, v3
	v_mul_f32_e32 v159, v159, v2
	v_pk_mul_f32 v[48:49], v[48:49], v[2:3] op_sel_hi:[1,0]
	v_pk_mul_f32 v[46:47], v[46:47], v[2:3] op_sel_hi:[1,0]
	v_pk_mul_f32 v[44:45], v[44:45], v[2:3] op_sel_hi:[1,0]
	v_pk_mul_f32 v[42:43], v[42:43], v[2:3] op_sel_hi:[1,0]
	v_pk_mul_f32 v[40:41], v[40:41], v[2:3] op_sel_hi:[1,0]
	v_pk_mul_f32 v[38:39], v[38:39], v[2:3] op_sel_hi:[1,0]
	v_pk_mul_f32 v[36:37], v[36:37], v[2:3] op_sel_hi:[1,0]
	v_pk_mul_f32 v[34:35], v[34:35], v[2:3] op_sel_hi:[1,0]
	v_pk_mul_f32 v[64:65], v[64:65], v[2:3] op_sel_hi:[1,0]
	v_pk_mul_f32 v[62:63], v[62:63], v[2:3] op_sel_hi:[1,0]
	v_pk_mul_f32 v[60:61], v[60:61], v[2:3] op_sel_hi:[1,0]
	v_pk_mul_f32 v[58:59], v[58:59], v[2:3] op_sel_hi:[1,0]
	v_pk_mul_f32 v[56:57], v[56:57], v[2:3] op_sel_hi:[1,0]
	v_pk_mul_f32 v[54:55], v[54:55], v[2:3] op_sel_hi:[1,0]
	v_pk_mul_f32 v[52:53], v[52:53], v[2:3] op_sel_hi:[1,0]
	v_pk_mul_f32 v[50:51], v[50:51], v[2:3] op_sel_hi:[1,0]

.LBB0_314:
	s_or_b64 exec, exec, s[8:9]
	v_max_f32_e32 v2, v2, v2
	s_mov_b32 s8, 0x41000000
	s_waitcnt lgkmcnt(0)
	v_mov_b32_e32 v3, v2
	s_nop 1
	v_permlane32_swap_b32_e32 v2, v3
	v_max_f32_e32 v2, v2, v3
	v_sub_f32_e32 v3, v2, v201
	v_cmp_lt_f32_e32 vcc, s8, v3
	s_cbranch_vccz .LBB0_316
	v_max_f32_e32 v2, v2, v2
	v_max_f32_e32 v3, v201, v201
	v_max_f32_e32 v3, v3, v2
	v_cmp_neq_f32_e32 vcc, s33, v3
	s_nop 1
	v_cndmask_b32_e32 v2, 0, v3, vcc
	v_sub_f32_e32 v2, v201, v2
	v_exp_f32_e32 v2, v2
	v_mov_b32_e32 v201, v3
	v_mul_f32_e32 v135, v135, v2
	v_pk_mul_f32 v[48:49], v[48:49], v[2:3] op_sel_hi:[1,0]
	v_pk_mul_f32 v[46:47], v[46:47], v[2:3] op_sel_hi:[1,0]
	v_pk_mul_f32 v[44:45], v[44:45], v[2:3] op_sel_hi:[1,0]
	v_pk_mul_f32 v[42:43], v[42:43], v[2:3] op_sel_hi:[1,0]
	v_pk_mul_f32 v[40:41], v[40:41], v[2:3] op_sel_hi:[1,0]
	v_pk_mul_f32 v[38:39], v[38:39], v[2:3] op_sel_hi:[1,0]
	v_pk_mul_f32 v[36:37], v[36:37], v[2:3] op_sel_hi:[1,0]
	v_pk_mul_f32 v[34:35], v[34:35], v[2:3] op_sel_hi:[1,0]
	v_pk_mul_f32 v[64:65], v[64:65], v[2:3] op_sel_hi:[1,0]
	v_pk_mul_f32 v[62:63], v[62:63], v[2:3] op_sel_hi:[1,0]
	v_pk_mul_f32 v[60:61], v[60:61], v[2:3] op_sel_hi:[1,0]
	v_pk_mul_f32 v[58:59], v[58:59], v[2:3] op_sel_hi:[1,0]
	v_pk_mul_f32 v[56:57], v[56:57], v[2:3] op_sel_hi:[1,0]
	v_pk_mul_f32 v[54:55], v[54:55], v[2:3] op_sel_hi:[1,0]
	v_pk_mul_f32 v[52:53], v[52:53], v[2:3] op_sel_hi:[1,0]
	v_pk_mul_f32 v[50:51], v[50:51], v[2:3] op_sel_hi:[1,0]

.LBB0_338:
	s_or_b64 exec, exec, s[8:9]
	v_max_f32_e32 v2, v2, v2
	s_mov_b32 s8, 0x41000000
	s_waitcnt lgkmcnt(0)
	v_mov_b32_e32 v3, v2
	s_nop 1
	v_permlane32_swap_b32_e32 v2, v3
	v_max_f32_e32 v2, v2, v3
	v_sub_f32_e32 v3, v2, v202
	v_cmp_lt_f32_e32 vcc, s8, v3
	s_cbranch_vccz .LBB0_340
	v_max_f32_e32 v2, v2, v2
	v_max_f32_e32 v3, v202, v202
	v_max_f32_e32 v3, v3, v2
	v_cmp_neq_f32_e32 vcc, s33, v3
	s_nop 1
	v_cndmask_b32_e32 v2, 0, v3, vcc
	v_sub_f32_e32 v2, v202, v2
	v_exp_f32_e32 v2, v2
	v_mov_b32_e32 v202, v3
	v_mul_f32_e32 v139, v139, v2
	v_pk_mul_f32 v[48:49], v[48:49], v[2:3] op_sel_hi:[1,0]
	v_pk_mul_f32 v[46:47], v[46:47], v[2:3] op_sel_hi:[1,0]
	v_pk_mul_f32 v[44:45], v[44:45], v[2:3] op_sel_hi:[1,0]
	v_pk_mul_f32 v[42:43], v[42:43], v[2:3] op_sel_hi:[1,0]
	v_pk_mul_f32 v[40:41], v[40:41], v[2:3] op_sel_hi:[1,0]
	v_pk_mul_f32 v[38:39], v[38:39], v[2:3] op_sel_hi:[1,0]
	v_pk_mul_f32 v[36:37], v[36:37], v[2:3] op_sel_hi:[1,0]
	v_pk_mul_f32 v[34:35], v[34:35], v[2:3] op_sel_hi:[1,0]
	v_pk_mul_f32 v[64:65], v[64:65], v[2:3] op_sel_hi:[1,0]
	v_pk_mul_f32 v[62:63], v[62:63], v[2:3] op_sel_hi:[1,0]
	v_pk_mul_f32 v[60:61], v[60:61], v[2:3] op_sel_hi:[1,0]
	v_pk_mul_f32 v[58:59], v[58:59], v[2:3] op_sel_hi:[1,0]
	v_pk_mul_f32 v[56:57], v[56:57], v[2:3] op_sel_hi:[1,0]
	v_pk_mul_f32 v[54:55], v[54:55], v[2:3] op_sel_hi:[1,0]
	v_pk_mul_f32 v[52:53], v[52:53], v[2:3] op_sel_hi:[1,0]
	v_pk_mul_f32 v[50:51], v[50:51], v[2:3] op_sel_hi:[1,0]

.LBB0_362:
	s_or_b64 exec, exec, s[8:9]
	v_max_f32_e32 v2, v2, v2
	s_mov_b32 s8, 0x41000000
	s_waitcnt lgkmcnt(0)
	v_mov_b32_e32 v3, v2
	s_nop 1
	v_permlane32_swap_b32_e32 v2, v3
	v_max_f32_e32 v2, v2, v3
	v_sub_f32_e32 v3, v2, v203
	v_cmp_lt_f32_e32 vcc, s8, v3
	s_cbranch_vccz .LBB0_364
	v_max_f32_e32 v2, v2, v2
	v_max_f32_e32 v3, v203, v203
	v_max_f32_e32 v3, v3, v2
	v_cmp_neq_f32_e32 vcc, s33, v3
	s_nop 1
	v_cndmask_b32_e32 v2, 0, v3, vcc
	v_sub_f32_e32 v2, v203, v2
	v_exp_f32_e32 v2, v2
	v_mov_b32_e32 v203, v3
	v_mul_f32_e32 v137, v137, v2
	v_pk_mul_f32 v[48:49], v[48:49], v[2:3] op_sel_hi:[1,0]
	v_pk_mul_f32 v[46:47], v[46:47], v[2:3] op_sel_hi:[1,0]
	v_pk_mul_f32 v[44:45], v[44:45], v[2:3] op_sel_hi:[1,0]
	v_pk_mul_f32 v[42:43], v[42:43], v[2:3] op_sel_hi:[1,0]
	v_pk_mul_f32 v[40:41], v[40:41], v[2:3] op_sel_hi:[1,0]
	v_pk_mul_f32 v[38:39], v[38:39], v[2:3] op_sel_hi:[1,0]
	v_pk_mul_f32 v[36:37], v[36:37], v[2:3] op_sel_hi:[1,0]
	v_pk_mul_f32 v[34:35], v[34:35], v[2:3] op_sel_hi:[1,0]
	v_pk_mul_f32 v[64:65], v[64:65], v[2:3] op_sel_hi:[1,0]
	v_pk_mul_f32 v[62:63], v[62:63], v[2:3] op_sel_hi:[1,0]
	v_pk_mul_f32 v[60:61], v[60:61], v[2:3] op_sel_hi:[1,0]
	v_pk_mul_f32 v[58:59], v[58:59], v[2:3] op_sel_hi:[1,0]
	v_pk_mul_f32 v[56:57], v[56:57], v[2:3] op_sel_hi:[1,0]
	v_pk_mul_f32 v[54:55], v[54:55], v[2:3] op_sel_hi:[1,0]
	v_pk_mul_f32 v[52:53], v[52:53], v[2:3] op_sel_hi:[1,0]
	v_pk_mul_f32 v[50:51], v[50:51], v[2:3] op_sel_hi:[1,0]

.LBB0_490:
	s_or_b64 exec, exec, s[0:1]
	v_and_b32_e32 v4, 64, v228
	v_xor_b32_e32 v3, 32, v228
	v_add_u32_e32 v4, 64, v4
	v_cmp_lt_i32_e32 vcc, v3, v4
	s_mov_b32 s0, 0x41000000
	s_nop 0
	v_cndmask_b32_e32 v3, v228, v3, vcc
	v_lshlrev_b32_e32 v3, 2, v3
	v_max_f32_e32 v2, v2, v2
	s_waitcnt lgkmcnt(0)
	v_mov_b32_e32 v3, v2
	s_nop 1
	v_permlane32_swap_b32_e32 v2, v3
	v_max_f32_e32 v2, v2, v3
	v_sub_f32_e32 v3, v2, v246
	v_cmp_lt_f32_e32 vcc, s0, v3
	s_cbranch_vccz .LBB0_492
	v_max_f32_e32 v2, v2, v2
	v_max_f32_e32 v3, v246, v246
	v_max_f32_e32 v3, v3, v2
	v_cmp_neq_f32_e32 vcc, s33, v3
	s_nop 1
	v_cndmask_b32_e32 v2, 0, v3, vcc
	v_sub_f32_e32 v2, v246, v2
	v_exp_f32_e32 v2, v2
	v_mov_b32_e32 v246, v3
	v_mul_f32_e32 v203, v203, v2
	v_pk_mul_f32 v[96:97], v[96:97], v[2:3] op_sel_hi:[1,0]
	v_pk_mul_f32 v[94:95], v[94:95], v[2:3] op_sel_hi:[1,0]
	v_pk_mul_f32 v[92:93], v[92:93], v[2:3] op_sel_hi:[1,0]
	v_pk_mul_f32 v[90:91], v[90:91], v[2:3] op_sel_hi:[1,0]
	v_pk_mul_f32 v[88:89], v[88:89], v[2:3] op_sel_hi:[1,0]
	v_pk_mul_f32 v[86:87], v[86:87], v[2:3] op_sel_hi:[1,0]
	v_pk_mul_f32 v[84:85], v[84:85], v[2:3] op_sel_hi:[1,0]
	v_pk_mul_f32 v[82:83], v[82:83], v[2:3] op_sel_hi:[1,0]
	v_pk_mul_f32 v[80:81], v[80:81], v[2:3] op_sel_hi:[1,0]
	v_pk_mul_f32 v[78:79], v[78:79], v[2:3] op_sel_hi:[1,0]
	v_pk_mul_f32 v[76:77], v[76:77], v[2:3] op_sel_hi:[1,0]
	v_pk_mul_f32 v[74:75], v[74:75], v[2:3] op_sel_hi:[1,0]
	v_pk_mul_f32 v[72:73], v[72:73], v[2:3] op_sel_hi:[1,0]
	v_pk_mul_f32 v[70:71], v[70:71], v[2:3] op_sel_hi:[1,0]
	v_pk_mul_f32 v[68:69], v[68:69], v[2:3] op_sel_hi:[1,0]
	v_pk_mul_f32 v[66:67], v[66:67], v[2:3] op_sel_hi:[1,0]
	v_pk_mul_f32 v[64:65], v[64:65], v[2:3] op_sel_hi:[1,0]
	v_pk_mul_f32 v[62:63], v[62:63], v[2:3] op_sel_hi:[1,0]
	v_pk_mul_f32 v[60:61], v[60:61], v[2:3] op_sel_hi:[1,0]
	v_pk_mul_f32 v[58:59], v[58:59], v[2:3] op_sel_hi:[1,0]
	v_pk_mul_f32 v[56:57], v[56:57], v[2:3] op_sel_hi:[1,0]
	v_pk_mul_f32 v[54:55], v[54:55], v[2:3] op_sel_hi:[1,0]
	v_pk_mul_f32 v[52:53], v[52:53], v[2:3] op_sel_hi:[1,0]
	v_pk_mul_f32 v[50:51], v[50:51], v[2:3] op_sel_hi:[1,0]
	v_pk_mul_f32 v[48:49], v[48:49], v[2:3] op_sel_hi:[1,0]
	v_pk_mul_f32 v[46:47], v[46:47], v[2:3] op_sel_hi:[1,0]
	v_pk_mul_f32 v[44:45], v[44:45], v[2:3] op_sel_hi:[1,0]
	v_pk_mul_f32 v[42:43], v[42:43], v[2:3] op_sel_hi:[1,0]
	v_pk_mul_f32 v[40:41], v[40:41], v[2:3] op_sel_hi:[1,0]
	v_pk_mul_f32 v[38:39], v[38:39], v[2:3] op_sel_hi:[1,0]
	v_pk_mul_f32 v[36:37], v[36:37], v[2:3] op_sel_hi:[1,0]
	v_pk_mul_f32 v[34:35], v[34:35], v[2:3] op_sel_hi:[1,0]

.LBB0_521:
	s_add_i32 s0, s54, -1
	s_and_b32 s55, s0, 1
	s_sub_i32 s0, s53, 63
	v_cmp_le_i32_e32 vcc, s0, v152
	v_cmp_ge_i32_e64 s[0:1], s53, v151
	v_cmp_lt_i32_e64 s[4:5], s53, v151
	s_and_b64 s[30:31], vcc, s[0:1]
	s_mov_b64 s[0:1], 0
	s_and_saveexec_b64 s[56:57], s[30:31]
	s_xor_b64 s[30:31], exec, s[56:57]
	s_cbranch_execz .LBB0_533
	s_mul_i32 s0, s55, 0x2400
	v_add_u32_e32 v0, s0, v153
	ds_read_b128 v[18:21], v0
	ds_read_b128 v[98:101], v0 offset:32
	ds_read_b128 v[2:5], v0 offset:4608
	ds_read_b128 v[22:25], v0 offset:4640
	ds_read_b128 v[102:105], v0 offset:64
	ds_read_b128 v[158:161], v0 offset:96
	ds_read_b128 v[26:29], v0 offset:4672
	ds_read_b128 v[30:33], v0 offset:4704
	s_waitcnt lgkmcnt(5)
	v_mfma_f32_32x32x16_bf16 v[2:17], v[2:5], v[66:69], 0
	s_mul_i32 s0, s55, 0x2200
	v_add_u32_e32 v0, s0, v154
	s_waitcnt lgkmcnt(4)
	v_mfma_f32_32x32x16_bf16 v[2:17], v[22:25], v[70:73], v[2:17]
	s_waitcnt lgkmcnt(1)
	v_mfma_f32_32x32x16_bf16 v[2:17], v[26:29], v[74:77], v[2:17]
	s_waitcnt lgkmcnt(0)
	v_mfma_f32_32x32x16_bf16 v[2:17], v[30:33], v[78:81], v[2:17]
	v_mfma_f32_32x32x16_bf16 v[18:33], v[18:21], v[66:69], 0
	v_mfma_f32_32x32x16_bf16 v[18:33], v[98:101], v[70:73], v[18:33]
	v_add_u32_e32 v98, 0x4800, v0
	v_mfma_f32_32x32x16_bf16 v[18:33], v[102:105], v[74:77], v[18:33]
	ds_read2_b64 v[110:113], v98 offset1:2
	ds_read2_b64 v[106:109], v98 offset0:4 offset1:6
	ds_read2_b64 v[102:105], v98 offset0:8 offset1:10
	ds_read2_b64 v[98:101], v98 offset0:12 offset1:14
	v_mfma_f32_32x32x16_bf16 v[18:33], v[158:161], v[78:81], v[18:33]
	s_movk_i32 s0, 0xffe1
	v_add3_u32 v163, v135, v155, s0
	v_add_u32_e32 v174, v156, v155
	v_subrev_u32_e32 v157, 31, v174
	v_subrev_u32_e32 v162, 32, v174
	v_sub_u32_e32 v173, v163, v117
	v_sub_u32_e32 v184, v163, v122
	v_med3_i32 v158, v157, 0, v229
	v_med3_i32 v159, v162, 0, v229
	v_med3_i32 v160, v184, 0, v229
	v_med3_i32 v161, v173, 0, v229
	v_sub_u32_e32 v177, v163, v119
	v_sub_u32_e32 v176, v163, v124
	v_sub_u32_e32 v179, v163, v121
	v_sub_u32_e32 v178, v163, v126
	v_lshlrev_b32_e32 v158, 2, v158
	v_lshlrev_b32_e32 v159, 2, v159
	v_lshlrev_b32_e32 v160, 2, v160
	v_lshlrev_b32_e32 v161, 2, v161
	v_med3_i32 v164, v176, 0, v229
	v_med3_i32 v165, v177, 0, v229
	v_med3_i32 v166, v178, 0, v229
	v_med3_i32 v167, v179, 0, v229
	v_lshlrev_b32_e32 v164, 2, v164
	v_lshlrev_b32_e32 v165, 2, v165
	v_lshlrev_b32_e32 v166, 2, v166
	v_lshlrev_b32_e32 v167, 2, v167
	ds_read_b32 v170, v158 offset:60000
	ds_read_b32 v171, v159 offset:60000
	ds_read_b32 v158, v160 offset:60000
	ds_read_b32 v159, v161 offset:60000
	ds_read_b32 v160, v164 offset:60000
	ds_read_b32 v161, v165 offset:60000
	ds_read_b32 v168, v166 offset:60000
	ds_read_b32 v169, v167 offset:60000
	s_movk_i32 s0, 0x80
	s_waitcnt lgkmcnt(7)
	v_fmac_f32_e32 v170, 0x3e38aa3b, v18
	v_cmp_gt_u32_e32 vcc, s0, v157
	s_waitcnt lgkmcnt(6)
	v_fmac_f32_e32 v171, 0x3e38aa3b, v19
	s_waitcnt lgkmcnt(4)
	v_pk_fma_f32 v[18:19], v[20:21], s[92:93], v[158:159] op_sel_hi:[1,0,1]
	v_cndmask_b32_e32 v167, v230, v170, vcc
	v_cmp_gt_u32_e32 vcc, s0, v162
	v_sub_u32_e32 v21, v163, v125
	v_sub_u32_e32 v185, v163, v129
	v_cndmask_b32_e32 v166, v230, v171, vcc
	v_cmp_gt_u32_e32 vcc, s0, v173
	v_max3_f32 v157, v167, s33, v166
	s_nop 0
	v_cndmask_b32_e32 v162, v230, v19, vcc
	v_cmp_gt_u32_e32 vcc, s0, v184
	s_nop 1
	v_cndmask_b32_e32 v165, v230, v18, vcc
	s_waitcnt lgkmcnt(2)
	v_pk_fma_f32 v[18:19], v[22:23], s[92:93], v[160:161] op_sel_hi:[1,0,1]
	v_cmp_gt_u32_e32 vcc, s0, v177
	v_max3_f32 v20, v157, v165, v162
	v_sub_u32_e32 v23, v163, v127
	v_cndmask_b32_e32 v158, v230, v19, vcc
	v_cmp_gt_u32_e32 vcc, s0, v176
	s_nop 1
	v_cndmask_b32_e32 v161, v230, v18, vcc
	s_waitcnt lgkmcnt(0)
	v_pk_fma_f32 v[18:19], v[24:25], s[92:93], v[168:169] op_sel_hi:[1,0,1]
	v_cmp_gt_u32_e32 vcc, s0, v179
	v_max3_f32 v20, v20, v161, v158
	v_med3_i32 v168, v185, 0, v229
	v_cndmask_b32_e32 v157, v230, v19, vcc
	v_cmp_gt_u32_e32 vcc, s0, v178
	v_sub_u32_e32 v19, v163, v123
	v_lshlrev_b32_e32 v183, 2, v168
	v_cndmask_b32_e32 v159, v230, v18, vcc
	v_sub_u32_e32 v18, v163, v128
	v_max3_f32 v25, v20, v159, v157
	v_med3_i32 v20, v18, 0, v229
	v_lshlrev_b32_e32 v160, 2, v20
	v_med3_i32 v20, v19, 0, v229
	v_lshlrev_b32_e32 v164, 2, v20
	v_sub_u32_e32 v20, v163, v130
	v_med3_i32 v22, v20, 0, v229
	v_lshlrev_b32_e32 v170, 2, v22
	v_med3_i32 v22, v21, 0, v229
	v_lshlrev_b32_e32 v171, 2, v22
	v_sub_u32_e32 v22, v163, v132
	v_med3_i32 v24, v22, 0, v229
	v_lshlrev_b32_e32 v172, 2, v24
	v_med3_i32 v24, v23, 0, v229
	v_lshlrev_b32_e32 v175, 2, v24
	v_sub_u32_e32 v24, v163, v134
	v_med3_i32 v163, v24, 0, v229
	v_lshlrev_b32_e32 v163, 2, v163
	ds_read_b32 v168, v160 offset:60000
	ds_read_b32 v169, v164 offset:60000
	ds_read_b32 v170, v170 offset:60000
	ds_read_b32 v171, v171 offset:60000
	ds_read_b32 v180, v172 offset:60000
	ds_read_b32 v181, v175 offset:60000
	ds_read_b32 v182, v163 offset:60000
	ds_read_b32 v183, v183 offset:60000
	s_waitcnt lgkmcnt(6)
	v_pk_fma_f32 v[26:27], v[26:27], s[92:93], v[168:169] op_sel_hi:[1,0,1]
	v_cmp_gt_u32_e32 vcc, s0, v19
	s_nop 1
	v_cndmask_b32_e32 v172, v230, v27, vcc
	v_cmp_gt_u32_e32 vcc, s0, v18
	s_nop 1
	v_cndmask_b32_e32 v175, v230, v26, vcc
	s_waitcnt lgkmcnt(4)
	v_pk_fma_f32 v[26:27], v[28:29], s[92:93], v[170:171] op_sel_hi:[1,0,1]
	v_cmp_gt_u32_e32 vcc, s0, v21
	v_subrev_u32_e32 v170, 63, v174
	v_subrev_u32_e32 v174, 64, v174
	v_cndmask_b32_e32 v169, v230, v27, vcc
	v_cmp_gt_u32_e32 vcc, s0, v20
	v_max3_f32 v25, v25, v175, v172
	s_nop 0
	v_cndmask_b32_e32 v171, v230, v26, vcc
	s_waitcnt lgkmcnt(2)
	v_pk_fma_f32 v[26:27], v[30:31], s[92:93], v[180:181] op_sel_hi:[1,0,1]
	v_cmp_gt_u32_e32 vcc, s0, v23
	v_subrev_u32_e32 v180, 32, v184
	v_max3_f32 v25, v25, v171, v169
	v_cndmask_b32_e32 v163, v230, v27, vcc
	v_cmp_gt_u32_e32 vcc, s0, v22
	s_nop 1
	v_cndmask_b32_e32 v168, v230, v26, vcc
	s_waitcnt lgkmcnt(0)
	v_pk_fma_f32 v[26:27], v[32:33], s[92:93], v[182:183] op_sel_hi:[1,0,1]
	v_cmp_gt_u32_e32 vcc, s0, v185
	v_max3_f32 v25, v25, v168, v163
	s_nop 0
	v_cndmask_b32_e32 v160, v230, v27, vcc
	v_cmp_gt_u32_e32 vcc, s0, v24
	s_nop 1
	v_cndmask_b32_e32 v164, v230, v26, vcc
	v_med3_i32 v26, v170, 0, v229
	v_lshlrev_b32_e32 v28, 2, v26
	v_med3_i32 v26, v174, 0, v229
	v_lshlrev_b32_e32 v29, 2, v26
	v_med3_i32 v26, v180, 0, v229
	v_lshlrev_b32_e32 v30, 2, v26
	v_pk_mov_b32 v[26:27], v[172:173], v[176:177] op_sel:[1,0]
	v_cmp_gt_u32_e32 vcc, s0, v170
	v_subrev_u32_e32 v182, 32, v26
	v_subrev_u32_e32 v173, 32, v27
	v_med3_i32 v26, v182, 0, v229
	v_lshlrev_b32_e32 v31, 2, v26
	v_med3_i32 v26, v173, 0, v229
	v_lshlrev_b32_e32 v32, 2, v26
	v_pk_mov_b32 v[26:27], v[176:177], v[178:179] op_sel:[1,0]
	v_max3_f32 v25, v25, v164, v160
	v_subrev_u32_e32 v184, 32, v26
	v_subrev_u32_e32 v183, 32, v27
	v_med3_i32 v26, v184, 0, v229
	v_lshlrev_b32_e32 v33, 2, v26
	v_med3_i32 v26, v183, 0, v229
	v_lshlrev_b32_e32 v176, 2, v26
	v_pk_mov_b32 v[26:27], v[178:179], v[18:19] op_sel:[1,0]
	s_nop 0
	v_subrev_u32_e32 v178, 32, v26
	v_med3_i32 v26, v178, 0, v229
	v_lshlrev_b32_e32 v26, 2, v26
	ds_read_b32 v177, v28 offset:60000
	ds_read_b32 v28, v29 offset:60000
	ds_read_b32 v29, v30 offset:60000
	ds_read_b32 v30, v31 offset:60000
	ds_read_b32 v31, v32 offset:60000
	ds_read_b32 v32, v33 offset:60000
	ds_read_b32 v33, v176 offset:60000
	ds_read_b32 v26, v26 offset:60000
	s_waitcnt lgkmcnt(7)
	v_fmac_f32_e32 v177, 0x3e38aa3b, v2
	v_mov_b32_e32 v2, v3
	v_mov_b32_e32 v3, v4
	v_cndmask_b32_e32 v181, v230, v177, vcc
	s_waitcnt lgkmcnt(5)
	v_pk_fma_f32 v[2:3], v[2:3], s[92:93], v[28:29] op_sel_hi:[1,0,1]
	v_cmp_gt_u32_e32 vcc, s0, v180
	v_subrev_u32_e32 v28, 32, v27
	s_nop 0
	v_cndmask_b32_e32 v177, v230, v3, vcc
	v_cmp_gt_u32_e32 vcc, s0, v174
	v_mov_b32_e32 v3, v6
	s_nop 0
	v_cndmask_b32_e32 v179, v230, v2, vcc
	v_mov_b32_e32 v2, v5
	s_waitcnt lgkmcnt(3)
	v_pk_fma_f32 v[2:3], v[2:3], s[92:93], v[30:31] op_sel_hi:[1,0,1]
	v_cmp_gt_u32_e32 vcc, s0, v173
	v_max3_f32 v4, v25, v181, v179
	v_subrev_u32_e32 v30, 32, v185
	v_cndmask_b32_e32 v173, v230, v3, vcc
	v_cmp_gt_u32_e32 vcc, s0, v182
	v_mov_b32_e32 v3, v8
	s_nop 0
	v_cndmask_b32_e32 v176, v230, v2, vcc
	v_mov_b32_e32 v2, v7
	s_waitcnt lgkmcnt(1)
	v_pk_fma_f32 v[2:3], v[2:3], s[92:93], v[32:33] op_sel_hi:[1,0,1]
	v_cmp_gt_u32_e32 vcc, s0, v183
	v_max3_f32 v4, v4, v177, v176
	s_nop 0
	v_cndmask_b32_e32 v170, v230, v3, vcc
	v_cmp_gt_u32_e32 vcc, s0, v184
	v_mov_b32_e32 v3, v10
	s_nop 0
	v_cndmask_b32_e32 v174, v230, v2, vcc
	v_max3_f32 v25, v4, v173, v174
	v_pk_mov_b32 v[4:5], v[18:19], v[20:21] op_sel:[1,0]
	v_med3_i32 v2, v28, 0, v229
	v_subrev_u32_e32 v18, 32, v4
	v_subrev_u32_e32 v10, 32, v5
	v_med3_i32 v4, v18, 0, v229
	v_lshlrev_b32_e32 v7, 2, v4
	v_med3_i32 v4, v10, 0, v229
	v_lshlrev_b32_e32 v8, 2, v4
	v_pk_mov_b32 v[4:5], v[20:21], v[22:23] op_sel:[1,0]
	v_lshlrev_b32_e32 v6, 2, v2
	v_subrev_u32_e32 v20, 32, v4
	v_subrev_u32_e32 v19, 32, v5
	v_med3_i32 v4, v20, 0, v229
	v_mov_b32_e32 v2, v9
	v_lshlrev_b32_e32 v9, 2, v4
	v_med3_i32 v4, v19, 0, v229
	v_lshlrev_b32_e32 v21, 2, v4
	v_pk_mov_b32 v[4:5], v[22:23], v[24:25] op_sel:[1,0]
	v_cmp_gt_u32_e32 vcc, s0, v28
	v_subrev_u32_e32 v23, 32, v4
	v_subrev_u32_e32 v22, 32, v5
	v_med3_i32 v4, v23, 0, v229
	v_lshlrev_b32_e32 v24, 2, v4
	v_med3_i32 v4, v22, 0, v229
	v_lshlrev_b32_e32 v29, 2, v4
	v_med3_i32 v4, v30, 0, v229
	v_lshlrev_b32_e32 v31, 2, v4
	ds_read_b32 v27, v6 offset:60000
	ds_read_b32 v4, v7 offset:60000
	ds_read_b32 v5, v8 offset:60000
	ds_read_b32 v6, v9 offset:60000
	ds_read_b32 v7, v21 offset:60000
	ds_read_b32 v8, v24 offset:60000
	ds_read_b32 v9, v29 offset:60000
	ds_read_b32 v21, v31 offset:60000
	s_waitcnt lgkmcnt(7)
	v_pk_fma_f32 v[2:3], v[2:3], s[92:93], v[26:27] op_sel_hi:[1,0,1]
	s_waitcnt lgkmcnt(0)
	v_fmac_f32_e32 v21, 0x3e38aa3b, v17
	v_cndmask_b32_e32 v186, v230, v3, vcc
	v_cmp_gt_u32_e32 vcc, s0, v178
	v_mov_b32_e32 v3, v12
	s_nop 0
	v_cndmask_b32_e32 v188, v230, v2, vcc
	v_mov_b32_e32 v2, v11
	v_pk_fma_f32 v[2:3], v[2:3], s[92:93], v[4:5] op_sel_hi:[1,0,1]
	v_cmp_gt_u32_e32 vcc, s0, v10
	v_max3_f32 v24, v25, v170, v188
	s_nop 0
	v_cndmask_b32_e32 v185, v230, v3, vcc
	v_cmp_gt_u32_e32 vcc, s0, v18
	v_mov_b32_e32 v3, v14
	s_nop 0
	v_cndmask_b32_e32 v187, v230, v2, vcc
	v_mov_b32_e32 v2, v13
	v_pk_fma_f32 v[2:3], v[2:3], s[92:93], v[6:7] op_sel_hi:[1,0,1]
	v_cmp_gt_u32_e32 vcc, s0, v19
	v_max3_f32 v4, v24, v186, v187
	s_nop 0
	v_cndmask_b32_e32 v182, v230, v3, vcc
	v_cmp_gt_u32_e32 vcc, s0, v20
	v_mov_b32_e32 v3, v16
	s_nop 0
	v_cndmask_b32_e32 v184, v230, v2, vcc
	v_mov_b32_e32 v2, v15
	v_pk_fma_f32 v[2:3], v[2:3], s[92:93], v[8:9] op_sel_hi:[1,0,1]
	v_cmp_gt_u32_e32 vcc, s0, v22
	v_max3_f32 v4, v4, v185, v184
	s_nop 0
	v_cndmask_b32_e32 v180, v230, v3, vcc
	v_cmp_gt_u32_e32 vcc, s0, v23
	v_xor_b32_e32 v3, 32, v228
	s_nop 0
	v_cndmask_b32_e32 v183, v230, v2, vcc
	v_max3_f32 v2, v4, v182, v183
	v_and_b32_e32 v4, 64, v228
	v_cmp_gt_u32_e32 vcc, s0, v30
	v_add_u32_e32 v4, 64, v4
	s_mov_b32 s0, 0x41000000
	v_cndmask_b32_e32 v178, v230, v21, vcc
	v_cmp_lt_i32_e32 vcc, v3, v4
	v_max3_f32 v2, v2, v180, v178
	s_nop 0
	v_cndmask_b32_e32 v3, v228, v3, vcc
	v_lshlrev_b32_e32 v3, 2, v3
	s_waitcnt lgkmcnt(0)
	v_mov_b32_e32 v3, v2
	s_nop 1
	v_permlane32_swap_b32_e32 v2, v3
	v_max_f32_e32 v2, v2, v3
	v_sub_f32_e32 v3, v2, v146
	v_cmp_lt_f32_e32 vcc, s0, v3
	s_cbranch_vccz .LBB0_524
	v_max_f32_e32 v2, v2, v2
	v_max_f32_e32 v3, v146, v146
	v_max_f32_e32 v3, v3, v2
	v_cmp_neq_f32_e32 vcc, s33, v3
	s_nop 1
	v_cndmask_b32_e32 v2, 0, v3, vcc
	v_sub_f32_e32 v2, v146, v2
	v_exp_f32_e32 v2, v2
	v_mov_b32_e32 v146, v3
	v_mul_f32_e32 v145, v145, v2
	v_pk_mul_f32 v[64:65], v[64:65], v[2:3] op_sel_hi:[1,0]
	v_pk_mul_f32 v[62:63], v[62:63], v[2:3] op_sel_hi:[1,0]
	v_pk_mul_f32 v[60:61], v[60:61], v[2:3] op_sel_hi:[1,0]
	v_pk_mul_f32 v[58:59], v[58:59], v[2:3] op_sel_hi:[1,0]
	v_pk_mul_f32 v[56:57], v[56:57], v[2:3] op_sel_hi:[1,0]
	v_pk_mul_f32 v[54:55], v[54:55], v[2:3] op_sel_hi:[1,0]
	v_pk_mul_f32 v[52:53], v[52:53], v[2:3] op_sel_hi:[1,0]
	v_pk_mul_f32 v[50:51], v[50:51], v[2:3] op_sel_hi:[1,0]
	v_pk_mul_f32 v[48:49], v[48:49], v[2:3] op_sel_hi:[1,0]
	v_pk_mul_f32 v[46:47], v[46:47], v[2:3] op_sel_hi:[1,0]
	v_pk_mul_f32 v[44:45], v[44:45], v[2:3] op_sel_hi:[1,0]
	v_pk_mul_f32 v[42:43], v[42:43], v[2:3] op_sel_hi:[1,0]
	v_pk_mul_f32 v[40:41], v[40:41], v[2:3] op_sel_hi:[1,0]
	v_pk_mul_f32 v[38:39], v[38:39], v[2:3] op_sel_hi:[1,0]
	v_pk_mul_f32 v[36:37], v[36:37], v[2:3] op_sel_hi:[1,0]
	v_pk_mul_f32 v[34:35], v[34:35], v[2:3] op_sel_hi:[1,0]
